# cache policy: down-proj epilogue residual loads use the default policy instead of nt
# speedup vs baseline: 1.0032x; 1.0028x over previous
;     __device__ __forceinline__ void operator()(Acc& acc, const Unit& u, int wr, int wc, int fr, int fq) const {
;     ...
; #pragma unroll
;         for (int ai = 0; ai < 2; ++ai) {
;             u32x2 res[4][2][2];
; #pragma unroll
;             for (int m = 0; m < 4; ++m) { const bf16_t* rp = xb + (size_t)(row0 + ai * HALF + m * 16) * DM + col0;
; #pragma unroll
;                 for (int bj = 0; bj < 2; ++bj)
; #pragma unroll
;                     for (int n = 0; n < 2; ++n) res[m][bj][n] = __builtin_nontemporal_load((const u32x2*)(rp + bj * HALF + n * 16)); }
; #pragma unroll
;             for (int m = 0; m < 4; ++m) { float* rp = Y + (size_t)(row0 + ai * HALF + m * 16) * DM + col0;
; #pragma unroll
;                 for (int bj = 0; bj < 2; ++bj)
; #pragma unroll
;                     for (int n = 0; n < 2; ++n) { const u32x2 w = res[m][bj][n];
;                         *(f32x4*)(rp + bj * HALF + n * 16) = (f32x4){bflo(w.x), bfhi(w.x), bflo(w.y), bfhi(w.y)} + acc[ai][bj][m][n]; } }
.LBB0_1200:
	v_mov_b32_e32 v138, v148
	v_mov_b32_e32 v139, v149
	s_lshl_b32 s15, s43, 8
	s_add_i32 s15, s15, s34
	v_add_u32_e32 v138, s15, v138
	s_lshl_b32 s15, s44, 8
	s_or_b32 s15, s15, s35
	v_lshl_add_u32 v140, v139, 2, s15
	s_mov_b64 s[20:21], -1
	s_cmpk_gt_i32 s43, 0x7f
	v_ashrrev_i32_e32 v141, 31, v140
	s_cbranch_scc1 .LBB0_1203
	v_ashrrev_i32_e32 v139, 31, v138
	v_lshl_add_u64 v[144:145], v[140:141], 1, s[76:77]
	v_lshlrev_b64 v[142:143], 11, v[138:139]
	v_add_u32_e32 v162, 16, v138
	v_lshl_add_u64 v[142:143], v[144:145], 0, v[142:143]
	v_ashrrev_i32_e32 v163, 31, v162
	global_load_dwordx2 v[154:155], v[142:143], off
	global_load_dwordx2 v[156:157], v[142:143], off offset:32
	global_load_dwordx2 v[158:159], v[142:143], off offset:256
	global_load_dwordx2 v[160:161], v[142:143], off offset:288
	v_lshlrev_b64 v[142:143], 11, v[162:163]
	v_lshl_add_u64 v[142:143], v[144:145], 0, v[142:143]
	global_load_dwordx2 v[170:171], v[142:143], off
	global_load_dwordx2 v[172:173], v[142:143], off offset:32
	global_load_dwordx2 v[174:175], v[142:143], off offset:256
	global_load_dwordx2 v[176:177], v[142:143], off offset:288
	v_add_u32_e32 v178, 32, v138
	v_ashrrev_i32_e32 v179, 31, v178
	v_lshlrev_b64 v[142:143], 11, v[178:179]
	v_lshl_add_u64 v[164:165], v[144:145], 0, v[142:143]
	global_load_dwordx2 v[180:181], v[164:165], off
	global_load_dwordx2 v[182:183], v[164:165], off offset:32
	v_add_u32_e32 v146, 48, v138
	v_ashrrev_i32_e32 v147, 31, v146
	v_lshlrev_b64 v[168:169], 11, v[146:147]
	v_lshl_add_u64 v[168:169], v[144:145], 0, v[168:169]
	global_load_dwordx2 v[186:187], v[164:165], off offset:256
	global_load_dwordx2 v[188:189], v[164:165], off offset:288
	global_load_dwordx2 v[190:191], v[168:169], off
	global_load_dwordx2 v[192:193], v[168:169], off offset:32
	global_load_dwordx2 v[194:195], v[168:169], off offset:256
	global_load_dwordx2 v[196:197], v[168:169], off offset:288
	v_lshlrev_b64 v[162:163], 12, v[162:163]
	v_lshlrev_b64 v[142:143], 2, v[140:141]
	v_lshlrev_b64 v[166:167], 12, v[138:139]
	v_lshl_add_u64 v[162:163], s[6:7], 0, v[162:163]
	v_lshl_add_u64 v[166:167], s[6:7], 0, v[166:167]
	v_lshl_add_u64 v[198:199], v[162:163], 0, v[142:143]
	v_lshl_add_u64 v[184:185], v[166:167], 0, v[142:143]
	v_lshlrev_b64 v[146:147], 12, v[146:147]
	v_lshl_add_u64 v[146:147], s[6:7], 0, v[146:147]
	v_lshl_add_u64 v[146:147], v[146:147], 0, v[142:143]
	s_waitcnt vmcnt(0)
	v_lshlrev_b32_e32 v162, 16, v154
	v_and_b32_e32 v163, 0xffff0000, v154
	v_lshlrev_b32_e32 v154, 16, v155
	v_and_b32_e32 v155, 0xffff0000, v155
	v_lshlrev_b32_e32 v164, 16, v156
	v_and_b32_e32 v165, 0xffff0000, v156
	v_lshlrev_b32_e32 v200, 16, v159
	v_and_b32_e32 v201, 0xffff0000, v159
	v_lshlrev_b32_e32 v166, 16, v157
	v_and_b32_e32 v167, 0xffff0000, v157
	v_lshlrev_b32_e32 v168, 16, v158
	v_and_b32_e32 v169, 0xffff0000, v158
	v_lshlrev_b32_e32 v202, 16, v160
	v_and_b32_e32 v203, 0xffff0000, v160
	v_lshlrev_b32_e32 v204, 16, v161
	v_and_b32_e32 v205, 0xffff0000, v161
	v_pk_add_f32 v[156:157], v[126:127], v[154:155]
	v_pk_add_f32 v[154:155], v[124:125], v[162:163]
	v_pk_add_f32 v[158:159], v[120:121], v[164:165]
	v_pk_add_f32 v[164:165], v[110:111], v[200:201]
	v_lshlrev_b32_e32 v200, 16, v170
	v_and_b32_e32 v201, 0xffff0000, v170
	v_lshlrev_b32_e32 v170, 16, v171
	v_and_b32_e32 v171, 0xffff0000, v171
	v_pk_add_f32 v[160:161], v[122:123], v[166:167]
	v_pk_add_f32 v[162:163], v[108:109], v[168:169]
	v_pk_add_f32 v[168:169], v[102:103], v[204:205]
	v_pk_add_f32 v[166:167], v[100:101], v[202:203]
	v_lshlrev_b32_e32 v202, 16, v172
	v_and_b32_e32 v203, 0xffff0000, v172
	v_lshlrev_b32_e32 v172, 16, v173
	v_and_b32_e32 v173, 0xffff0000, v173
	v_lshlrev_b32_e32 v204, 16, v174
	v_and_b32_e32 v205, 0xffff0000, v174
	v_lshlrev_b32_e32 v174, 16, v175
	v_and_b32_e32 v175, 0xffff0000, v175
	global_store_dwordx4 v[184:185], v[154:157], off
	global_store_dwordx4 v[184:185], v[158:161], off offset:64
	global_store_dwordx4 v[184:185], v[162:165], off offset:512
	global_store_dwordx4 v[184:185], v[166:169], off offset:576
	v_pk_add_f32 v[156:157], v[118:119], v[170:171]
	v_pk_add_f32 v[154:155], v[116:117], v[200:201]
	v_pk_add_f32 v[160:161], v[114:115], v[172:173]
	v_pk_add_f32 v[158:159], v[112:113], v[202:203]
	v_pk_add_f32 v[164:165], v[94:95], v[174:175]
	v_pk_add_f32 v[162:163], v[92:93], v[204:205]
	global_store_dwordx4 v[198:199], v[154:157], off
	global_store_dwordx4 v[198:199], v[158:161], off offset:64
	global_store_dwordx4 v[198:199], v[162:165], off offset:512
	v_lshlrev_b32_e32 v154, 16, v176
	v_and_b32_e32 v155, 0xffff0000, v176
	v_lshlrev_b32_e32 v156, 16, v177
	v_and_b32_e32 v157, 0xffff0000, v177
	v_pk_add_f32 v[156:157], v[86:87], v[156:157]
	v_pk_add_f32 v[154:155], v[84:85], v[154:155]
	global_store_dwordx4 v[198:199], v[154:157], off offset:576
	v_add_u32_e32 v164, 0x90, v138
	v_ashrrev_i32_e32 v165, 31, v164
	v_lshlrev_b64 v[154:155], 12, v[178:179]
	v_lshl_add_u64 v[154:155], s[6:7], 0, v[154:155]
	v_lshl_add_u64 v[158:159], v[154:155], 0, v[142:143]
	v_lshlrev_b32_e32 v154, 16, v180
	v_and_b32_e32 v155, 0xffff0000, v180
	v_lshlrev_b32_e32 v156, 16, v181
	v_and_b32_e32 v157, 0xffff0000, v181
	v_pk_add_f32 v[156:157], v[106:107], v[156:157]
	v_pk_add_f32 v[154:155], v[104:105], v[154:155]
	global_store_dwordx4 v[158:159], v[154:157], off
	v_add_u32_e32 v174, 0xa0, v138
	v_ashrrev_i32_e32 v175, 31, v174
	v_lshlrev_b32_e32 v154, 16, v182
	v_and_b32_e32 v155, 0xffff0000, v182
	v_lshlrev_b32_e32 v156, 16, v183
	v_and_b32_e32 v157, 0xffff0000, v183
	v_pk_add_f32 v[156:157], v[98:99], v[156:157]
	v_pk_add_f32 v[154:155], v[96:97], v[154:155]
;     __device__ __forceinline__ void operator()(Acc& acc, const Unit& u, int wr, int wc, int fr, int fq) const {
;     ...
; #pragma unroll
;         for (int ai = 0; ai < 2; ++ai) {
;             u32x2 res[4][2][2];
; #pragma unroll
;             for (int m = 0; m < 4; ++m) { const bf16_t* rp = xb + (size_t)(row0 + ai * HALF + m * 16) * DM + col0;
; #pragma unroll
;                 for (int bj = 0; bj < 2; ++bj)
; #pragma unroll
;                     for (int n = 0; n < 2; ++n) res[m][bj][n] = __builtin_nontemporal_load((const u32x2*)(rp + bj * HALF + n * 16)); }
; #pragma unroll
;             for (int m = 0; m < 4; ++m) { float* rp = Y + (size_t)(row0 + ai * HALF + m * 16) * DM + col0;
; #pragma unroll
;                 for (int bj = 0; bj < 2; ++bj)
; #pragma unroll
;                     for (int n = 0; n < 2; ++n) { const u32x2 w = res[m][bj][n];
;                         *(f32x4*)(rp + bj * HALF + n * 16) = (f32x4){bflo(w.x), bfhi(w.x), bflo(w.y), bfhi(w.y)} + acc[ai][bj][m][n]; } }
;             asm volatile("" ::: "memory"); }
	global_store_dwordx4 v[158:159], v[154:157], off offset:64
	v_add_u32_e32 v184, 0xb0, v138
	v_ashrrev_i32_e32 v185, 31, v184
	v_lshlrev_b32_e32 v154, 16, v186
	v_and_b32_e32 v155, 0xffff0000, v186
	v_lshlrev_b32_e32 v156, 16, v187
	v_and_b32_e32 v157, 0xffff0000, v187
	v_pk_add_f32 v[156:157], v[78:79], v[156:157]
	v_pk_add_f32 v[154:155], v[76:77], v[154:155]
	global_store_dwordx4 v[158:159], v[154:157], off offset:512
	s_nop 1
	v_lshlrev_b32_e32 v154, 16, v188
	v_and_b32_e32 v155, 0xffff0000, v188
	v_lshlrev_b32_e32 v156, 16, v189
	v_and_b32_e32 v157, 0xffff0000, v189
	v_pk_add_f32 v[156:157], v[74:75], v[156:157]
	v_pk_add_f32 v[154:155], v[72:73], v[154:155]
	global_store_dwordx4 v[158:159], v[154:157], off offset:576
	s_nop 1
	v_lshlrev_b32_e32 v154, 16, v190
	v_and_b32_e32 v155, 0xffff0000, v190
	v_lshlrev_b32_e32 v156, 16, v191
	v_and_b32_e32 v157, 0xffff0000, v191
	v_pk_add_f32 v[156:157], v[90:91], v[156:157]
	v_pk_add_f32 v[154:155], v[88:89], v[154:155]
	global_store_dwordx4 v[146:147], v[154:157], off
	s_nop 1
	v_lshlrev_b32_e32 v154, 16, v192
	v_and_b32_e32 v155, 0xffff0000, v192
	v_lshlrev_b32_e32 v156, 16, v193
	v_and_b32_e32 v157, 0xffff0000, v193
	v_pk_add_f32 v[156:157], v[82:83], v[156:157]
	v_pk_add_f32 v[154:155], v[80:81], v[154:155]
	global_store_dwordx4 v[146:147], v[154:157], off offset:64
	s_nop 1
	v_lshlrev_b32_e32 v154, 16, v194
	v_and_b32_e32 v155, 0xffff0000, v194
	v_lshlrev_b32_e32 v156, 16, v195
	v_and_b32_e32 v157, 0xffff0000, v195
	v_pk_add_f32 v[156:157], v[70:71], v[156:157]
	v_pk_add_f32 v[154:155], v[68:69], v[154:155]
	global_store_dwordx4 v[146:147], v[154:157], off offset:512
	s_nop 1
	v_lshlrev_b32_e32 v154, 16, v196
	v_and_b32_e32 v155, 0xffff0000, v196
	v_lshlrev_b32_e32 v156, 16, v197
	v_and_b32_e32 v157, 0xffff0000, v197
	v_pk_add_f32 v[156:157], v[66:67], v[156:157]
	v_pk_add_f32 v[154:155], v[64:65], v[154:155]
	global_store_dwordx4 v[146:147], v[154:157], off offset:576
	s_nop 1
	v_add_u32_e32 v154, 0x80, v138
	v_ashrrev_i32_e32 v155, 31, v154
	v_lshlrev_b64 v[146:147], 11, v[154:155]
	v_lshl_add_u64 v[146:147], v[144:145], 0, v[146:147]
	global_load_dwordx2 v[156:157], v[146:147], off
	global_load_dwordx2 v[158:159], v[146:147], off offset:32
	global_load_dwordx2 v[160:161], v[146:147], off offset:256
	global_load_dwordx2 v[162:163], v[146:147], off offset:288
	v_lshlrev_b64 v[146:147], 11, v[164:165]
	v_lshl_add_u64 v[146:147], v[144:145], 0, v[146:147]
	global_load_dwordx2 v[166:167], v[146:147], off
	global_load_dwordx2 v[168:169], v[146:147], off offset:32
	global_load_dwordx2 v[170:171], v[146:147], off offset:256
	global_load_dwordx2 v[172:173], v[146:147], off offset:288
	v_lshlrev_b64 v[146:147], 11, v[174:175]
	v_lshl_add_u64 v[146:147], v[144:145], 0, v[146:147]
	global_load_dwordx2 v[176:177], v[146:147], off
	global_load_dwordx2 v[178:179], v[146:147], off offset:32
	global_load_dwordx2 v[180:181], v[146:147], off offset:256
	global_load_dwordx2 v[182:183], v[146:147], off offset:288
	v_lshlrev_b64 v[146:147], 11, v[184:185]
	v_lshl_add_u64 v[144:145], v[144:145], 0, v[146:147]
	global_load_dwordx2 v[186:187], v[144:145], off
	global_load_dwordx2 v[188:189], v[144:145], off offset:32
	global_load_dwordx2 v[146:147], v[144:145], off offset:256
	s_nop 0
	global_load_dwordx2 v[144:145], v[144:145], off offset:288
	v_lshlrev_b64 v[154:155], 12, v[154:155]
	v_lshl_add_u64 v[154:155], s[6:7], 0, v[154:155]
	v_lshl_add_u64 v[190:191], v[154:155], 0, v[142:143]
	s_waitcnt vmcnt(15)
	v_lshlrev_b32_e32 v154, 16, v156
	v_and_b32_e32 v155, 0xffff0000, v156
	v_lshlrev_b32_e32 v156, 16, v157
	v_and_b32_e32 v157, 0xffff0000, v157
	v_pk_add_f32 v[156:157], v[62:63], v[156:157]
	v_pk_add_f32 v[154:155], v[60:61], v[154:155]
	global_store_dwordx4 v[190:191], v[154:157], off
	s_waitcnt vmcnt(15)
	s_nop 0
	v_lshlrev_b32_e32 v154, 16, v158
	v_and_b32_e32 v155, 0xffff0000, v158
	v_lshlrev_b32_e32 v156, 16, v159
	v_and_b32_e32 v157, 0xffff0000, v159
	v_pk_add_f32 v[156:157], v[58:59], v[156:157]
	v_pk_add_f32 v[154:155], v[56:57], v[154:155]
	global_store_dwordx4 v[190:191], v[154:157], off offset:64
	s_waitcnt vmcnt(15)
	s_nop 0
	v_lshlrev_b32_e32 v154, 16, v160
	v_and_b32_e32 v155, 0xffff0000, v160
	v_lshlrev_b32_e32 v156, 16, v161
	v_and_b32_e32 v157, 0xffff0000, v161
	v_pk_add_f32 v[156:157], v[46:47], v[156:157]
	v_pk_add_f32 v[154:155], v[44:45], v[154:155]
	global_store_dwordx4 v[190:191], v[154:157], off offset:512
	s_waitcnt vmcnt(15)
;     __device__ __forceinline__ void operator()(Acc& acc, const Unit& u, int wr, int wc, int fr, int fq) const {
;     ...
;             for (int m = 0; m < 4; ++m) { float* rp = Y + (size_t)(row0 + ai * HALF + m * 16) * DM + col0;
; #pragma unroll
;                 for (int bj = 0; bj < 2; ++bj)
; #pragma unroll
;                     for (int n = 0; n < 2; ++n) { const u32x2 w = res[m][bj][n];
;                         *(f32x4*)(rp + bj * HALF + n * 16) = (f32x4){bflo(w.x), bfhi(w.x), bflo(w.y), bfhi(w.y)} + acc[ai][bj][m][n]; } }
	s_nop 0
	v_lshlrev_b32_e32 v154, 16, v162
	v_and_b32_e32 v155, 0xffff0000, v162
	v_lshlrev_b32_e32 v156, 16, v163
	v_and_b32_e32 v157, 0xffff0000, v163
	v_pk_add_f32 v[156:157], v[38:39], v[156:157]
	v_pk_add_f32 v[154:155], v[36:37], v[154:155]
	global_store_dwordx4 v[190:191], v[154:157], off offset:576
	s_nop 1
	v_lshlrev_b64 v[154:155], 12, v[164:165]
	v_lshl_add_u64 v[154:155], s[6:7], 0, v[154:155]
	v_lshl_add_u64 v[158:159], v[154:155], 0, v[142:143]
	s_waitcnt vmcnt(15)
	v_lshlrev_b32_e32 v154, 16, v166
	v_and_b32_e32 v155, 0xffff0000, v166
	v_lshlrev_b32_e32 v156, 16, v167
	v_and_b32_e32 v157, 0xffff0000, v167
	v_pk_add_f32 v[156:157], v[54:55], v[156:157]
	v_pk_add_f32 v[154:155], v[52:53], v[154:155]
	global_store_dwordx4 v[158:159], v[154:157], off
	s_waitcnt vmcnt(15)
	s_nop 0
	v_lshlrev_b32_e32 v154, 16, v168
	v_and_b32_e32 v155, 0xffff0000, v168
	v_lshlrev_b32_e32 v156, 16, v169
	v_and_b32_e32 v157, 0xffff0000, v169
	v_pk_add_f32 v[156:157], v[50:51], v[156:157]
	v_pk_add_f32 v[154:155], v[48:49], v[154:155]
	global_store_dwordx4 v[158:159], v[154:157], off offset:64
	s_waitcnt vmcnt(15)
	s_nop 0
	v_lshlrev_b32_e32 v154, 16, v170
	v_and_b32_e32 v155, 0xffff0000, v170
	v_lshlrev_b32_e32 v156, 16, v171
	v_and_b32_e32 v157, 0xffff0000, v171
	v_pk_add_f32 v[156:157], v[30:31], v[156:157]
	v_pk_add_f32 v[154:155], v[28:29], v[154:155]
	global_store_dwordx4 v[158:159], v[154:157], off offset:512
	s_waitcnt vmcnt(15)
	s_nop 0
	v_lshlrev_b32_e32 v154, 16, v172
	v_and_b32_e32 v155, 0xffff0000, v172
	v_lshlrev_b32_e32 v156, 16, v173
	v_and_b32_e32 v157, 0xffff0000, v173
	v_pk_add_f32 v[156:157], v[22:23], v[156:157]
	v_pk_add_f32 v[154:155], v[20:21], v[154:155]
	global_store_dwordx4 v[158:159], v[154:157], off offset:576
	s_nop 1
	v_lshlrev_b64 v[154:155], 12, v[174:175]
	v_lshl_add_u64 v[154:155], s[6:7], 0, v[154:155]
	v_lshl_add_u64 v[158:159], v[154:155], 0, v[142:143]
	s_waitcnt vmcnt(15)
	v_lshlrev_b32_e32 v154, 16, v176
	v_and_b32_e32 v155, 0xffff0000, v176
	v_lshlrev_b32_e32 v156, 16, v177
	v_and_b32_e32 v157, 0xffff0000, v177
	v_pk_add_f32 v[156:157], v[42:43], v[156:157]
	v_pk_add_f32 v[154:155], v[40:41], v[154:155]
	global_store_dwordx4 v[158:159], v[154:157], off
	s_waitcnt vmcnt(15)
	s_nop 0
	v_lshlrev_b32_e32 v154, 16, v178
	v_and_b32_e32 v155, 0xffff0000, v178
	v_lshlrev_b32_e32 v156, 16, v179
	v_and_b32_e32 v157, 0xffff0000, v179
	v_pk_add_f32 v[156:157], v[34:35], v[156:157]
	v_pk_add_f32 v[154:155], v[32:33], v[154:155]
	global_store_dwordx4 v[158:159], v[154:157], off offset:64
	s_waitcnt vmcnt(15)
	s_nop 0
	v_lshlrev_b32_e32 v154, 16, v180
	v_and_b32_e32 v155, 0xffff0000, v180
	v_lshlrev_b32_e32 v156, 16, v181
	v_and_b32_e32 v157, 0xffff0000, v181
	v_pk_add_f32 v[156:157], v[14:15], v[156:157]
	v_pk_add_f32 v[154:155], v[12:13], v[154:155]
	global_store_dwordx4 v[158:159], v[154:157], off offset:512
	s_waitcnt vmcnt(15)
	s_nop 0
	v_lshlrev_b32_e32 v154, 16, v182
	v_and_b32_e32 v155, 0xffff0000, v182
	v_lshlrev_b32_e32 v156, 16, v183
	v_and_b32_e32 v157, 0xffff0000, v183
	v_pk_add_f32 v[156:157], v[10:11], v[156:157]
	v_pk_add_f32 v[154:155], v[8:9], v[154:155]
	global_store_dwordx4 v[158:159], v[154:157], off offset:576
	s_nop 1
	v_lshlrev_b64 v[154:155], 12, v[184:185]
	v_lshl_add_u64 v[154:155], s[6:7], 0, v[154:155]
	v_lshl_add_u64 v[158:159], v[154:155], 0, v[142:143]
	s_waitcnt vmcnt(15)
	v_lshlrev_b32_e32 v142, 16, v186
	v_and_b32_e32 v143, 0xffff0000, v186
	v_lshlrev_b32_e32 v154, 16, v187
	v_and_b32_e32 v155, 0xffff0000, v187
	v_pk_add_f32 v[156:157], v[26:27], v[154:155]
	v_pk_add_f32 v[154:155], v[24:25], v[142:143]
	global_store_dwordx4 v[158:159], v[154:157], off
	s_waitcnt vmcnt(15)
	v_lshlrev_b32_e32 v142, 16, v188
	v_and_b32_e32 v143, 0xffff0000, v188
	v_lshlrev_b32_e32 v154, 16, v189
	v_and_b32_e32 v155, 0xffff0000, v189
	v_pk_add_f32 v[156:157], v[18:19], v[154:155]
	v_pk_add_f32 v[154:155], v[16:17], v[142:143]
	s_waitcnt vmcnt(14)
	v_lshlrev_b32_e32 v142, 16, v146
	v_and_b32_e32 v143, 0xffff0000, v146
	global_store_dwordx4 v[158:159], v[154:157], off offset:64
	v_lshlrev_b32_e32 v146, 16, v147
	v_and_b32_e32 v147, 0xffff0000, v147
	v_pk_add_f32 v[154:155], v[4:5], v[142:143]
	s_waitcnt vmcnt(14)
	v_lshlrev_b32_e32 v142, 16, v144
	v_and_b32_e32 v143, 0xffff0000, v144
	v_lshlrev_b32_e32 v144, 16, v145
	v_and_b32_e32 v145, 0xffff0000, v145
	v_pk_add_f32 v[156:157], v[6:7], v[146:147]
	v_pk_add_f32 v[144:145], v[2:3], v[144:145]
	v_pk_add_f32 v[142:143], v[0:1], v[142:143]
	global_store_dwordx4 v[158:159], v[154:157], off offset:512
	global_store_dwordx4 v[158:159], v[142:145], off offset:576
	s_cbranch_execz .LBB0_1204
